# P2 epilogue: gate-bias vector loaded once per tile instead of 8 load+full-wait round trips
# speedup vs baseline: 1.0243x; 1.0030x over previous
.LBB0_347:
	v_mbcnt_lo_u32_b32 v144, -1, 0
	v_mbcnt_hi_u32_b32 v144, -1, v144
	v_readlane_b32 s9, v254, 61
	v_cvt_pk_bf16_f32 v124, v124, v125
	v_cvt_pk_bf16_f32 v125, v126, v127
	v_and_or_b32 v145, v144, 15, s9
	v_lshrrev_b32_e32 v144, 1, v144
	s_lshl_b32 s9, s20, 8
	v_readlane_b32 s20, v255, 10
	v_and_or_b32 v144, v144, 24, s9
	v_readlane_b32 s9, v255, 0
	v_readlane_b32 s21, v255, 11
	v_lshl_add_u32 v146, s22, 8, v145
	v_or_b32_e32 v144, s9, v144
	v_cvt_pk_bf16_f32 v126, v120, v121
	v_mov_b64_e32 v[120:121], s[20:21]
	v_mad_i64_i32 v[120:121], s[20:21], v146, s40, v[120:121]
	v_ashrrev_i32_e32 v145, 31, v144
	s_movk_i32 s9, 0x820
	v_ashrrev_i32_e32 v147, 31, v146
	v_cvt_pk_bf16_f32 v127, v122, v123
	v_lshl_add_u64 v[152:153], v[144:145], 1, v[120:121]
	v_cvt_pk_bf16_f32 v120, v112, v113
	v_cvt_pk_bf16_f32 v121, v114, v115
	v_cvt_pk_bf16_f32 v122, v104, v105
	v_cvt_pk_bf16_f32 v123, v106, v107
	v_cmp_eq_u32_e32 vcc, s9, v144
	global_store_dwordx4 v[152:153], v[124:127], off
	global_store_dwordx4 v[152:153], v[120:123], off offset:256
	s_and_saveexec_b64 s[20:21], vcc
	s_cbranch_execz .LBB0_349
	v_readlane_b32 s44, v254, 31
	v_readlane_b32 s45, v254, 32
	v_readlane_b32 s46, v254, 33
	v_readlane_b32 s47, v254, 34
	v_readlane_b32 s48, v254, 35
	v_readlane_b32 s49, v254, 36
	v_readlane_b32 s50, v254, 37
	v_readlane_b32 s51, v254, 38
	v_readlane_b32 s52, v254, 39
	v_readlane_b32 s53, v254, 40
	v_readlane_b32 s54, v254, 41
	v_readlane_b32 s55, v254, 42
	v_readlane_b32 s56, v254, 43
	v_readlane_b32 s57, v254, 44
	v_readlane_b32 s58, v254, 45
	v_readlane_b32 s59, v254, 46
	s_mov_b64 s[44:45], s[52:53]
	s_mov_b64 s[46:47], s[54:55]
	global_load_dwordx4 v[244:247], v131, s[46:47]
	global_load_dwordx4 v[248:251], v131, s[46:47] offset:16
	v_readlane_b32 s24, v255, 8
	v_lshlrev_b64 v[152:153], 5, v[146:147]
	v_readlane_b32 s25, v255, 9
	s_mov_b64 s[48:49], s[56:57]
	s_mov_b64 s[50:51], s[58:59]
	v_lshl_add_u64 v[152:153], s[24:25], 0, v[152:153]
	s_waitcnt vmcnt(0)
	v_mov_b32_e32 v120, v244
	v_mov_b32_e32 v121, v245
	v_mov_b32_e32 v122, v246
	v_mov_b32_e32 v123, v247
	v_mov_b32_e32 v124, v248
	v_mov_b32_e32 v125, v249
	v_mov_b32_e32 v126, v250
	v_mov_b32_e32 v127, v251
	v_pk_add_f32 v[114:115], v[114:115], v[122:123]
	v_pk_add_f32 v[112:113], v[112:113], v[120:121]
	v_pk_add_f32 v[106:107], v[106:107], v[126:127]
	v_pk_add_f32 v[104:105], v[104:105], v[124:125]
	global_store_dwordx4 v[152:153], v[112:115], off
	global_store_dwordx4 v[152:153], v[104:107], off offset:16
.LBB0_349:
	s_or_b64 exec, exec, s[20:21]
	v_readlane_b32 s20, v255, 10
	v_readlane_b32 s21, v255, 11
	v_or_b32_e32 v104, 16, v146
	v_cvt_pk_bf16_f32 v108, v108, v109
	v_cvt_pk_bf16_f32 v109, v110, v111
	v_mov_b64_e32 v[110:111], s[20:21]
	v_mad_i64_i32 v[110:111], s[20:21], v104, s40, v[110:111]
	v_cvt_pk_bf16_f32 v106, v116, v117
	v_cvt_pk_bf16_f32 v107, v118, v119
	v_lshl_add_u64 v[110:111], v[144:145], 1, v[110:111]
	global_store_dwordx4 v[110:111], v[106:109], off
	s_nop 1
	v_cvt_pk_bf16_f32 v106, v96, v97
	v_cvt_pk_bf16_f32 v107, v98, v99
	v_cvt_pk_bf16_f32 v108, v88, v89
	v_cvt_pk_bf16_f32 v109, v90, v91
	global_store_dwordx4 v[110:111], v[106:109], off offset:256
	s_and_saveexec_b64 s[20:21], vcc
	s_cbranch_execz .LBB0_351
	v_readlane_b32 s44, v254, 31
	v_readlane_b32 s45, v254, 32
	v_readlane_b32 s46, v254, 33
	v_readlane_b32 s47, v254, 34
	v_readlane_b32 s48, v254, 35
	v_readlane_b32 s49, v254, 36
	v_readlane_b32 s50, v254, 37
	v_readlane_b32 s51, v254, 38
	v_readlane_b32 s52, v254, 39
	v_readlane_b32 s53, v254, 40
	v_readlane_b32 s54, v254, 41
	v_readlane_b32 s55, v254, 42
	v_readlane_b32 s56, v254, 43
	v_readlane_b32 s57, v254, 44
	v_readlane_b32 s58, v254, 45
	v_readlane_b32 s59, v254, 46
	s_mov_b64 s[44:45], s[52:53]
	s_mov_b64 s[46:47], s[54:55]
	v_mov_b32_e32 v106, v244
	v_mov_b32_e32 v107, v245
	v_mov_b32_e32 v108, v246
	v_mov_b32_e32 v109, v247
	v_mov_b32_e32 v110, v248
	v_mov_b32_e32 v111, v249
	v_mov_b32_e32 v112, v250
	v_mov_b32_e32 v113, v251
	v_ashrrev_i32_e32 v105, 31, v104
	v_readlane_b32 s24, v255, 8
	v_lshlrev_b64 v[104:105], 5, v[104:105]
	v_readlane_b32 s25, v255, 9
	s_mov_b64 s[48:49], s[56:57]
	s_mov_b64 s[50:51], s[58:59]
	v_lshl_add_u64 v[104:105], s[24:25], 0, v[104:105]
	v_pk_add_f32 v[98:99], v[98:99], v[108:109]
	v_pk_add_f32 v[96:97], v[96:97], v[106:107]
	v_pk_add_f32 v[90:91], v[90:91], v[112:113]
	v_pk_add_f32 v[88:89], v[88:89], v[110:111]
	global_store_dwordx4 v[104:105], v[96:99], off
	global_store_dwordx4 v[104:105], v[88:91], off offset:16
.LBB0_351:
	s_or_b64 exec, exec, s[20:21]
	v_readlane_b32 s20, v255, 10
	v_readlane_b32 s21, v255, 11
	v_or_b32_e32 v88, 32, v146
	v_cvt_pk_bf16_f32 v92, v92, v93
	v_cvt_pk_bf16_f32 v93, v94, v95
	v_mov_b64_e32 v[94:95], s[20:21]
	v_mad_i64_i32 v[94:95], s[20:21], v88, s40, v[94:95]
	v_cvt_pk_bf16_f32 v90, v100, v101
	v_cvt_pk_bf16_f32 v91, v102, v103
	v_lshl_add_u64 v[94:95], v[144:145], 1, v[94:95]
	global_store_dwordx4 v[94:95], v[90:93], off
	s_nop 1
	v_cvt_pk_bf16_f32 v90, v80, v81
	v_cvt_pk_bf16_f32 v91, v82, v83
	v_cvt_pk_bf16_f32 v92, v72, v73
	v_cvt_pk_bf16_f32 v93, v74, v75
	global_store_dwordx4 v[94:95], v[90:93], off offset:256
	s_and_saveexec_b64 s[20:21], vcc
	s_cbranch_execz .LBB0_353
	v_readlane_b32 s44, v254, 31
	v_readlane_b32 s45, v254, 32
	v_readlane_b32 s46, v254, 33
	v_readlane_b32 s47, v254, 34
	v_readlane_b32 s48, v254, 35
	v_readlane_b32 s49, v254, 36
	v_readlane_b32 s50, v254, 37
	v_readlane_b32 s51, v254, 38
	v_readlane_b32 s52, v254, 39
	v_readlane_b32 s53, v254, 40
	v_readlane_b32 s54, v254, 41
	v_readlane_b32 s55, v254, 42
	v_readlane_b32 s56, v254, 43
	v_readlane_b32 s57, v254, 44
	v_readlane_b32 s58, v254, 45
	v_readlane_b32 s59, v254, 46
	s_mov_b64 s[44:45], s[52:53]
	s_mov_b64 s[46:47], s[54:55]
	v_mov_b32_e32 v90, v244
	v_mov_b32_e32 v91, v245
	v_mov_b32_e32 v92, v246
	v_mov_b32_e32 v93, v247
	v_mov_b32_e32 v94, v248
	v_mov_b32_e32 v95, v249
	v_mov_b32_e32 v96, v250
	v_mov_b32_e32 v97, v251
	v_ashrrev_i32_e32 v89, 31, v88
	v_readlane_b32 s24, v255, 8
	v_lshlrev_b64 v[88:89], 5, v[88:89]
	v_readlane_b32 s25, v255, 9
	s_mov_b64 s[48:49], s[56:57]
	s_mov_b64 s[50:51], s[58:59]
	v_lshl_add_u64 v[88:89], s[24:25], 0, v[88:89]
	v_pk_add_f32 v[82:83], v[82:83], v[92:93]
	v_pk_add_f32 v[80:81], v[80:81], v[90:91]
	v_pk_add_f32 v[74:75], v[74:75], v[96:97]
	v_pk_add_f32 v[72:73], v[72:73], v[94:95]
	global_store_dwordx4 v[88:89], v[80:83], off
	global_store_dwordx4 v[88:89], v[72:75], off offset:16
.LBB0_353:
	s_or_b64 exec, exec, s[20:21]
	v_readlane_b32 s20, v255, 10
	v_readlane_b32 s21, v255, 11
	v_or_b32_e32 v72, 48, v146
	v_cvt_pk_bf16_f32 v76, v76, v77
	v_cvt_pk_bf16_f32 v77, v78, v79
	v_mov_b64_e32 v[78:79], s[20:21]
	v_mad_i64_i32 v[78:79], s[20:21], v72, s40, v[78:79]
	v_cvt_pk_bf16_f32 v74, v84, v85
	v_cvt_pk_bf16_f32 v75, v86, v87
	v_lshl_add_u64 v[78:79], v[144:145], 1, v[78:79]
	global_store_dwordx4 v[78:79], v[74:77], off
	s_nop 1
	v_cvt_pk_bf16_f32 v74, v68, v69
	v_cvt_pk_bf16_f32 v75, v70, v71
	v_cvt_pk_bf16_f32 v76, v64, v65
	v_cvt_pk_bf16_f32 v77, v66, v67
	global_store_dwordx4 v[78:79], v[74:77], off offset:256
	s_and_saveexec_b64 s[20:21], vcc
	s_cbranch_execz .LBB0_355
	v_readlane_b32 s44, v254, 31
	v_readlane_b32 s45, v254, 32
	v_readlane_b32 s46, v254, 33
	v_readlane_b32 s47, v254, 34
	v_readlane_b32 s48, v254, 35
	v_readlane_b32 s49, v254, 36
	v_readlane_b32 s50, v254, 37
	v_readlane_b32 s51, v254, 38
	v_readlane_b32 s52, v254, 39
	v_readlane_b32 s53, v254, 40
	v_readlane_b32 s54, v254, 41
	v_readlane_b32 s55, v254, 42
	v_readlane_b32 s56, v254, 43
	v_readlane_b32 s57, v254, 44
	v_readlane_b32 s58, v254, 45
	v_readlane_b32 s59, v254, 46
	s_mov_b64 s[44:45], s[52:53]
	s_mov_b64 s[46:47], s[54:55]
	v_mov_b32_e32 v74, v244
	v_mov_b32_e32 v75, v245
	v_mov_b32_e32 v76, v246
	v_mov_b32_e32 v77, v247
	v_mov_b32_e32 v78, v248
	v_mov_b32_e32 v79, v249
	v_mov_b32_e32 v80, v250
	v_mov_b32_e32 v81, v251
	v_ashrrev_i32_e32 v73, 31, v72
	v_readlane_b32 s24, v255, 8
	v_lshlrev_b64 v[72:73], 5, v[72:73]
	v_readlane_b32 s25, v255, 9
	s_mov_b64 s[48:49], s[56:57]
	s_mov_b64 s[50:51], s[58:59]
	v_lshl_add_u64 v[72:73], s[24:25], 0, v[72:73]
	v_pk_add_f32 v[70:71], v[70:71], v[76:77]
	v_pk_add_f32 v[68:69], v[68:69], v[74:75]
	v_pk_add_f32 v[66:67], v[66:67], v[80:81]
	v_pk_add_f32 v[64:65], v[64:65], v[78:79]
	global_store_dwordx4 v[72:73], v[68:71], off
	global_store_dwordx4 v[72:73], v[64:67], off offset:16
.LBB0_355:
	s_or_b64 exec, exec, s[20:21]
	v_readlane_b32 s20, v255, 10
	v_readlane_b32 s21, v255, 11
	v_add_u32_e32 v64, 0x80, v146
	v_cvt_pk_bf16_f32 v60, v60, v61
	v_cvt_pk_bf16_f32 v61, v62, v63
	v_cvt_pk_bf16_f32 v62, v56, v57
	v_mov_b64_e32 v[56:57], s[20:21]
	v_mad_i64_i32 v[56:57], s[20:21], v64, s40, v[56:57]
	v_cvt_pk_bf16_f32 v63, v58, v59
	v_lshl_add_u64 v[66:67], v[144:145], 1, v[56:57]
	v_cvt_pk_bf16_f32 v56, v48, v49
	v_cvt_pk_bf16_f32 v57, v50, v51
	v_cvt_pk_bf16_f32 v58, v40, v41
	v_cvt_pk_bf16_f32 v59, v42, v43
	global_store_dwordx4 v[66:67], v[60:63], off
	global_store_dwordx4 v[66:67], v[56:59], off offset:256
	s_and_saveexec_b64 s[20:21], vcc
	s_cbranch_execz .LBB0_357
	v_readlane_b32 s44, v254, 31
	v_readlane_b32 s45, v254, 32
	v_readlane_b32 s46, v254, 33
	v_readlane_b32 s47, v254, 34
	v_readlane_b32 s48, v254, 35
	v_readlane_b32 s49, v254, 36
	v_readlane_b32 s50, v254, 37
	v_readlane_b32 s51, v254, 38
	v_readlane_b32 s52, v254, 39
	v_readlane_b32 s53, v254, 40
	v_readlane_b32 s54, v254, 41
	v_readlane_b32 s55, v254, 42
	v_readlane_b32 s56, v254, 43
	v_readlane_b32 s57, v254, 44
	v_readlane_b32 s58, v254, 45
	v_readlane_b32 s59, v254, 46
	s_mov_b64 s[44:45], s[52:53]
	s_mov_b64 s[46:47], s[54:55]
	v_mov_b32_e32 v56, v244
	v_mov_b32_e32 v57, v245
	v_mov_b32_e32 v58, v246
	v_mov_b32_e32 v59, v247
	v_mov_b32_e32 v60, v248
	v_mov_b32_e32 v61, v249
	v_mov_b32_e32 v62, v250
	v_mov_b32_e32 v63, v251
	v_ashrrev_i32_e32 v65, 31, v64
	v_readlane_b32 s24, v255, 8
	v_lshlrev_b64 v[64:65], 5, v[64:65]
	v_readlane_b32 s25, v255, 9
	s_mov_b64 s[48:49], s[56:57]
	s_mov_b64 s[50:51], s[58:59]
	v_lshl_add_u64 v[64:65], s[24:25], 0, v[64:65]
	v_pk_add_f32 v[50:51], v[50:51], v[58:59]
	v_pk_add_f32 v[48:49], v[48:49], v[56:57]
	v_pk_add_f32 v[42:43], v[42:43], v[62:63]
	v_pk_add_f32 v[40:41], v[40:41], v[60:61]
	global_store_dwordx4 v[64:65], v[48:51], off
	global_store_dwordx4 v[64:65], v[40:43], off offset:16
.LBB0_357:
	s_or_b64 exec, exec, s[20:21]
	v_readlane_b32 s20, v255, 10
	v_readlane_b32 s21, v255, 11
	v_add_u32_e32 v40, 0x90, v146
	v_cvt_pk_bf16_f32 v44, v44, v45
	v_cvt_pk_bf16_f32 v45, v46, v47
	v_mov_b64_e32 v[46:47], s[20:21]
	v_mad_i64_i32 v[46:47], s[20:21], v40, s40, v[46:47]
	v_cvt_pk_bf16_f32 v42, v52, v53
	v_cvt_pk_bf16_f32 v43, v54, v55
	v_lshl_add_u64 v[46:47], v[144:145], 1, v[46:47]
	global_store_dwordx4 v[46:47], v[42:45], off
	s_nop 1
	v_cvt_pk_bf16_f32 v42, v32, v33
	v_cvt_pk_bf16_f32 v43, v34, v35
	v_cvt_pk_bf16_f32 v44, v24, v25
	v_cvt_pk_bf16_f32 v45, v26, v27
	global_store_dwordx4 v[46:47], v[42:45], off offset:256
	s_and_saveexec_b64 s[20:21], vcc
	s_cbranch_execz .LBB0_359
	v_readlane_b32 s44, v254, 31
	v_readlane_b32 s45, v254, 32
	v_readlane_b32 s46, v254, 33
	v_readlane_b32 s47, v254, 34
	v_readlane_b32 s48, v254, 35
	v_readlane_b32 s49, v254, 36
	v_readlane_b32 s50, v254, 37
	v_readlane_b32 s51, v254, 38
	v_readlane_b32 s52, v254, 39
	v_readlane_b32 s53, v254, 40
	v_readlane_b32 s54, v254, 41
	v_readlane_b32 s55, v254, 42
	v_readlane_b32 s56, v254, 43
	v_readlane_b32 s57, v254, 44
	v_readlane_b32 s58, v254, 45
	v_readlane_b32 s59, v254, 46
	s_mov_b64 s[44:45], s[52:53]
	s_mov_b64 s[46:47], s[54:55]
	v_mov_b32_e32 v42, v244
	v_mov_b32_e32 v43, v245
	v_mov_b32_e32 v44, v246
	v_mov_b32_e32 v45, v247
	v_mov_b32_e32 v46, v248
	v_mov_b32_e32 v47, v249
	v_mov_b32_e32 v48, v250
	v_mov_b32_e32 v49, v251
	v_ashrrev_i32_e32 v41, 31, v40
	v_readlane_b32 s24, v255, 8
	v_lshlrev_b64 v[40:41], 5, v[40:41]
	v_readlane_b32 s25, v255, 9
	s_mov_b64 s[48:49], s[56:57]
	s_mov_b64 s[50:51], s[58:59]
	v_lshl_add_u64 v[40:41], s[24:25], 0, v[40:41]
	v_pk_add_f32 v[34:35], v[34:35], v[44:45]
	v_pk_add_f32 v[32:33], v[32:33], v[42:43]
	v_pk_add_f32 v[26:27], v[26:27], v[48:49]
	v_pk_add_f32 v[24:25], v[24:25], v[46:47]
	global_store_dwordx4 v[40:41], v[32:35], off
	global_store_dwordx4 v[40:41], v[24:27], off offset:16
.LBB0_359:
	s_or_b64 exec, exec, s[20:21]
	v_readlane_b32 s20, v255, 10
	v_readlane_b32 s21, v255, 11
	v_add_u32_e32 v24, 0xa0, v146
	v_cvt_pk_bf16_f32 v28, v28, v29
	v_cvt_pk_bf16_f32 v29, v30, v31
	v_mov_b64_e32 v[30:31], s[20:21]
	v_mad_i64_i32 v[30:31], s[20:21], v24, s40, v[30:31]
	v_cvt_pk_bf16_f32 v26, v36, v37
	v_cvt_pk_bf16_f32 v27, v38, v39
	v_lshl_add_u64 v[30:31], v[144:145], 1, v[30:31]
	global_store_dwordx4 v[30:31], v[26:29], off
	s_nop 1
	v_cvt_pk_bf16_f32 v26, v16, v17
	v_cvt_pk_bf16_f32 v27, v18, v19
	v_cvt_pk_bf16_f32 v28, v8, v9
	v_cvt_pk_bf16_f32 v29, v10, v11
	global_store_dwordx4 v[30:31], v[26:29], off offset:256
	s_and_saveexec_b64 s[20:21], vcc
	s_cbranch_execz .LBB0_361
	v_readlane_b32 s44, v254, 31
	v_readlane_b32 s45, v254, 32
	v_readlane_b32 s46, v254, 33
	v_readlane_b32 s47, v254, 34
	v_readlane_b32 s48, v254, 35
	v_readlane_b32 s49, v254, 36
	v_readlane_b32 s50, v254, 37
	v_readlane_b32 s51, v254, 38
	v_readlane_b32 s52, v254, 39
	v_readlane_b32 s53, v254, 40
	v_readlane_b32 s54, v254, 41
	v_readlane_b32 s55, v254, 42
	v_readlane_b32 s56, v254, 43
	v_readlane_b32 s57, v254, 44
	v_readlane_b32 s58, v254, 45
	v_readlane_b32 s59, v254, 46
	s_mov_b64 s[44:45], s[52:53]
	s_mov_b64 s[46:47], s[54:55]
	v_mov_b32_e32 v26, v244
	v_mov_b32_e32 v27, v245
	v_mov_b32_e32 v28, v246
	v_mov_b32_e32 v29, v247
	v_mov_b32_e32 v30, v248
	v_mov_b32_e32 v31, v249
	v_mov_b32_e32 v32, v250
	v_mov_b32_e32 v33, v251
	v_ashrrev_i32_e32 v25, 31, v24
	v_readlane_b32 s24, v255, 8
	v_lshlrev_b64 v[24:25], 5, v[24:25]
	v_readlane_b32 s25, v255, 9
	s_mov_b64 s[48:49], s[56:57]
	s_mov_b64 s[50:51], s[58:59]
	v_lshl_add_u64 v[24:25], s[24:25], 0, v[24:25]
	v_pk_add_f32 v[18:19], v[18:19], v[28:29]
	v_pk_add_f32 v[16:17], v[16:17], v[26:27]
	v_pk_add_f32 v[10:11], v[10:11], v[32:33]
	v_pk_add_f32 v[8:9], v[8:9], v[30:31]
	global_store_dwordx4 v[24:25], v[16:19], off
	global_store_dwordx4 v[24:25], v[8:11], off offset:16
.LBB0_361:
	s_or_b64 exec, exec, s[20:21]
	v_readlane_b32 s20, v255, 10
	v_readlane_b32 s21, v255, 11
	v_add_u32_e32 v8, 0xb0, v146
	v_cvt_pk_bf16_f32 v12, v12, v13
	v_cvt_pk_bf16_f32 v13, v14, v15
	v_mov_b64_e32 v[14:15], s[20:21]
	v_mad_i64_i32 v[14:15], s[20:21], v8, s40, v[14:15]
	v_cvt_pk_bf16_f32 v10, v20, v21
	v_cvt_pk_bf16_f32 v11, v22, v23
	v_lshl_add_u64 v[14:15], v[144:145], 1, v[14:15]
	global_store_dwordx4 v[14:15], v[10:13], off
	s_nop 1
	v_cvt_pk_bf16_f32 v10, v4, v5
	v_cvt_pk_bf16_f32 v11, v6, v7
	v_cvt_pk_bf16_f32 v12, v0, v1
	v_cvt_pk_bf16_f32 v13, v2, v3
	global_store_dwordx4 v[14:15], v[10:13], off offset:256
	s_and_saveexec_b64 s[20:21], vcc
	s_cbranch_execz .LBB0_363
	v_readlane_b32 s44, v254, 31
	v_readlane_b32 s45, v254, 32
	v_readlane_b32 s46, v254, 33
	v_readlane_b32 s47, v254, 34
	v_readlane_b32 s48, v254, 35
	v_readlane_b32 s49, v254, 36
	v_readlane_b32 s50, v254, 37
	v_readlane_b32 s51, v254, 38
	v_readlane_b32 s52, v254, 39
	v_readlane_b32 s53, v254, 40
	v_readlane_b32 s54, v254, 41
	v_readlane_b32 s55, v254, 42
	v_readlane_b32 s56, v254, 43
	v_readlane_b32 s57, v254, 44
	v_readlane_b32 s58, v254, 45
	v_readlane_b32 s59, v254, 46
	s_mov_b64 s[44:45], s[52:53]
	s_mov_b64 s[46:47], s[54:55]
	v_mov_b32_e32 v10, v244
	v_mov_b32_e32 v11, v245
	v_mov_b32_e32 v12, v246
	v_mov_b32_e32 v13, v247
	v_mov_b32_e32 v14, v248
	v_mov_b32_e32 v15, v249
	v_mov_b32_e32 v16, v250
	v_mov_b32_e32 v17, v251
	v_ashrrev_i32_e32 v9, 31, v8
	v_readlane_b32 s24, v255, 8
	v_lshlrev_b64 v[8:9], 5, v[8:9]
	v_readlane_b32 s25, v255, 9
	s_mov_b64 s[48:49], s[56:57]
	s_mov_b64 s[50:51], s[58:59]
	v_lshl_add_u64 v[8:9], s[24:25], 0, v[8:9]
	v_pk_add_f32 v[6:7], v[6:7], v[12:13]
	v_pk_add_f32 v[4:5], v[4:5], v[10:11]
	v_pk_add_f32 v[2:3], v[2:3], v[16:17]
	v_pk_add_f32 v[0:1], v[0:1], v[14:15]
	global_store_dwordx4 v[8:9], v[4:7], off
	global_store_dwordx4 v[8:9], v[0:3], off offset:16
